# GEMM K-loop: per-cluster s_setprio toggles removed, one static priority raise for the trailing wave half (waves 4-7) per unit
# speedup vs baseline: 1.0011x; 1.0011x over previous
; #define PG8_STAGE(bufoff, gbase, voff) do { _Pragma("unroll") for (int _i = 0; _i < 2; ++_i) \
;         __builtin_amdgcn_global_load_lds((const unsigned*)((const char*)(gbase) + (voff)[_i]), (PG8_LAS unsigned*)(lds + (bufoff) + ldsw + _i * 8192), 16, 0, 0); } while (0)
; #define PG8_LDA(dst, b, h) do { _Pragma("unroll") for (int m = 0; m < 4; ++m) _Pragma("unroll") for (int k = 0; k < 2; ++k) dst[m][k] = *(const PG8_LAS bf16x8*)(lds + PG8_SA(b, h) + aoff + m * 2048 + k * 1024); } while (0)
; #define PG8_LDB(dst, b, h) do { _Pragma("unroll") for (int n = 0; n < 2; ++n) _Pragma("unroll") for (int k = 0; k < 2; ++k) dst[n][k] = *(const PG8_LAS bf16x8*)(lds + PG8_SB(b, h) + boff + n * 2048 + k * 1024); } while (0)
; #define PG8_MMA(ai, bj, At, Bt) do { __builtin_amdgcn_s_setprio(1); _Pragma("unroll") for (int m = 0; m < 4; ++m) _Pragma("unroll") for (int n = 0; n < 2; ++n) _Pragma("unroll") for (int k = 0; k < 2; ++k) \
;         acc[ai][bj][m][n] = __builtin_amdgcn_mfma_f32_16x16x32_bf16(Bt[n][k], At[m][k], acc[ai][bj][m][n], 0, 0, 0); __builtin_amdgcn_s_setprio(0); } while (0)
; #define PG8_WAIT_V(n) asm volatile("s_waitcnt vmcnt(" #n ")" ::: "memory")
; #define PG8_WAIT_L(n) asm volatile("s_waitcnt lgkmcnt(" #n ")" ::: "memory")
; #define PG8_BAR __builtin_amdgcn_s_barrier()
; #define PG8_SCHED __builtin_amdgcn_sched_barrier(0)
; template <class Epi, class Sched, bool ALIGN_EPI = false, bool SP2 = false>
; __device__ __forceinline__ void gemm_phase(PG8_LAS unsigned char* lds, const Gemm g, const Sched& S, const Epi& E) {
;     ...
;             if constexpr (SP2) {
;             PG8_LDB(B0, 0, 0); PG8_LDB(B1, 0, 1); PG8_SCHED; PG8_LDA(At, 0, 0); PG8_STAGE(PG8_SA(1, 1), a1 + hstep, voffA);
;             PG8_WAIT_V(8); PG8_WAIT_L(0); PG8_BAR; PG8_MMA(0, 0, At, B0); PG8_MMA(0, 1, At, B1); PG8_BAR; PG8_SCHED;
;     ...
; #pragma unroll
;         for (int a = 0; a < 2; ++a)
; #pragma unroll
;             for (int b = 0; b < 2; ++b)
; #pragma unroll
;                 for (int m = 0; m < 4; ++m)
; #pragma unroll
;                     for (int n = 0; n < 2; ++n) acc[a][b][m][n] = (f32x4){0.f, 0.f, 0.f, 0.f};
.LBB0_185:
	s_add_u32 s12, s12, 0x80
	s_addc_u32 s13, s13, 0
	s_add_u32 s16, s14, 0x100
	v_mov_b32_e32 v0, 0
	s_addc_u32 s17, s15, 0
	s_mov_b32 s0, 0
	v_mov_b32_e32 v1, v0
	v_mov_b32_e32 v2, v0
	v_mov_b32_e32 v3, v0
	v_mov_b32_e32 v4, v0
	v_mov_b32_e32 v5, v0
	v_mov_b32_e32 v6, v0
	v_mov_b32_e32 v7, v0
	v_mov_b32_e32 v8, v0
	v_mov_b32_e32 v9, v0
	v_mov_b32_e32 v10, v0
	v_mov_b32_e32 v11, v0
	v_mov_b32_e32 v16, v0
	v_mov_b32_e32 v17, v0
	v_mov_b32_e32 v18, v0
	v_mov_b32_e32 v19, v0
	v_mov_b32_e32 v24, v0
	v_mov_b32_e32 v25, v0
	v_mov_b32_e32 v26, v0
	v_mov_b32_e32 v27, v0
	v_mov_b32_e32 v32, v0
	v_mov_b32_e32 v33, v0
	v_mov_b32_e32 v34, v0
	v_mov_b32_e32 v35, v0
	v_mov_b32_e32 v40, v0
	v_mov_b32_e32 v41, v0
	v_mov_b32_e32 v42, v0
	v_mov_b32_e32 v43, v0
	v_mov_b32_e32 v48, v0
	v_mov_b32_e32 v49, v0
	v_mov_b32_e32 v50, v0
	v_mov_b32_e32 v51, v0
	v_mov_b32_e32 v12, v0
	v_mov_b32_e32 v13, v0
	v_mov_b32_e32 v14, v0
	v_mov_b32_e32 v15, v0
	v_mov_b32_e32 v20, v0
	v_mov_b32_e32 v21, v0
	v_mov_b32_e32 v22, v0
	v_mov_b32_e32 v23, v0
	v_mov_b32_e32 v28, v0
	v_mov_b32_e32 v29, v0
	v_mov_b32_e32 v30, v0
	v_mov_b32_e32 v31, v0
	v_mov_b32_e32 v36, v0
	v_mov_b32_e32 v37, v0
	v_mov_b32_e32 v38, v0
	v_mov_b32_e32 v39, v0
	v_mov_b32_e32 v44, v0
	v_mov_b32_e32 v45, v0
	v_mov_b32_e32 v46, v0
	v_mov_b32_e32 v47, v0
	v_mov_b32_e32 v52, v0
	v_mov_b32_e32 v53, v0
	v_mov_b32_e32 v54, v0
	v_mov_b32_e32 v55, v0
	v_mov_b32_e32 v56, v0
	v_mov_b32_e32 v57, v0
	v_mov_b32_e32 v58, v0
	v_mov_b32_e32 v59, v0
	v_mov_b32_e32 v60, v0
	v_mov_b32_e32 v61, v0
	v_mov_b32_e32 v62, v0
	v_mov_b32_e32 v63, v0
	v_mov_b32_e32 v64, v0
	v_mov_b32_e32 v65, v0
	v_mov_b32_e32 v66, v0
	v_mov_b32_e32 v67, v0
	v_mov_b32_e32 v68, v0
	v_mov_b32_e32 v69, v0
	v_mov_b32_e32 v70, v0
	v_mov_b32_e32 v71, v0
	v_mov_b32_e32 v72, v0
	v_mov_b32_e32 v73, v0
	v_mov_b32_e32 v74, v0
	v_mov_b32_e32 v75, v0
	v_mov_b32_e32 v76, v0
	v_mov_b32_e32 v77, v0
	v_mov_b32_e32 v78, v0
	v_mov_b32_e32 v79, v0
	v_mov_b32_e32 v88, v0
	v_mov_b32_e32 v89, v0
	v_mov_b32_e32 v90, v0
	v_mov_b32_e32 v91, v0
	v_mov_b32_e32 v92, v0
	v_mov_b32_e32 v93, v0
	v_mov_b32_e32 v94, v0
	v_mov_b32_e32 v95, v0
	v_mov_b32_e32 v104, v0
	v_mov_b32_e32 v105, v0
	v_mov_b32_e32 v106, v0
	v_mov_b32_e32 v107, v0
	v_mov_b32_e32 v108, v0
	v_mov_b32_e32 v109, v0
	v_mov_b32_e32 v110, v0
	v_mov_b32_e32 v111, v0
	v_mov_b32_e32 v80, v0
	v_mov_b32_e32 v81, v0
	v_mov_b32_e32 v82, v0
	v_mov_b32_e32 v83, v0
	v_mov_b32_e32 v84, v0
	v_mov_b32_e32 v85, v0
	v_mov_b32_e32 v86, v0
	v_mov_b32_e32 v87, v0
	v_mov_b32_e32 v96, v0
	v_mov_b32_e32 v97, v0
	v_mov_b32_e32 v98, v0
	v_mov_b32_e32 v99, v0
	v_mov_b32_e32 v100, v0
	v_mov_b32_e32 v101, v0
	v_mov_b32_e32 v102, v0
	v_mov_b32_e32 v103, v0
	v_mov_b32_e32 v112, v0
	v_mov_b32_e32 v113, v0
	v_mov_b32_e32 v114, v0
	v_mov_b32_e32 v115, v0
	v_mov_b32_e32 v116, v0
	v_mov_b32_e32 v117, v0
	v_mov_b32_e32 v118, v0
	v_mov_b32_e32 v119, v0
	v_mov_b32_e32 v120, v0
	v_mov_b32_e32 v121, v0
	v_mov_b32_e32 v122, v0
	v_mov_b32_e32 v123, v0
	v_mov_b32_e32 v124, v0
	v_mov_b32_e32 v125, v0
	v_mov_b32_e32 v126, v0
	v_mov_b32_e32 v127, v0
	s_and_b64 vcc, exec, s[92:93]
	s_cbranch_vccnz .Lgemm_prio_skip
	s_setprio 1
.Lgemm_prio_skip:
.LBB0_186:
	s_add_i32 s1, s0, 2
	s_add_u32 s2, s12, 0x80
	s_addc_u32 s3, s13, 0
	s_add_i32 s33, 0, 0x10000
	s_cmp_eq_u32 s29, s0
	s_cselect_b32 s15, s73, s3
	s_cselect_b32 s14, s72, s2
	s_cselect_b32 s3, s5, s17
	s_cselect_b32 s2, s4, s16
	s_add_i32 s0, 0, 0x14000
	v_add_u32_e32 v140, s33, v252
	v_add_u32_e32 v156, s0, v252
	s_waitcnt lgkmcnt(0)
	ds_read_b128 v[128:131], v140
	ds_read_b128 v[132:135], v140 offset:1024
	ds_read_b128 v[136:139], v140 offset:2048
	ds_read_b128 v[140:143], v140 offset:3072
	ds_read_b128 v[144:147], v156
	ds_read_b128 v[148:151], v156 offset:1024
	ds_read_b128 v[152:155], v156 offset:2048
	ds_read_b128 v[156:159], v156 offset:3072
	v_lshl_add_u64 v[192:193], s[12:13], 0, v[216:217]
	s_add_i32 m0, s20, 0xc000
	ds_read_b128 v[160:163], v246
	ds_read_b128 v[164:167], v246 offset:1024
	ds_read_b128 v[168:171], v246 offset:2048
	ds_read_b128 v[172:175], v246 offset:3072
	ds_read_b128 v[176:179], v246 offset:4096
	ds_read_b128 v[180:183], v246 offset:5120
	ds_read_b128 v[184:187], v246 offset:6144
	ds_read_b128 v[188:191], v246 offset:7168
	global_load_lds_dwordx4 v[192:193], off
	v_lshl_add_u64 v[192:193], s[12:13], 0, v[218:219]
	s_add_i32 m0, s20, 0xe000
	s_nop 0
	global_load_lds_dwordx4 v[192:193], off
	s_waitcnt vmcnt(8)
	s_waitcnt lgkmcnt(0)
	s_barrier
	s_waitcnt lgkmcnt(0)
	v_mfma_f32_16x16x32_bf16 v[124:127], v[128:131], v[160:163], v[124:127]
	v_mfma_f32_16x16x32_bf16 v[120:123], v[136:139], v[160:163], v[120:123]
	v_mfma_f32_16x16x32_bf16 v[116:119], v[128:131], v[168:171], v[116:119]
	v_mfma_f32_16x16x32_bf16 v[112:115], v[136:139], v[168:171], v[112:115]
	v_mfma_f32_16x16x32_bf16 v[100:103], v[128:131], v[176:179], v[100:103]
	v_mfma_f32_16x16x32_bf16 v[96:99], v[136:139], v[176:179], v[96:99]
	v_mfma_f32_16x16x32_bf16 v[84:87], v[128:131], v[184:187], v[84:87]
	v_mfma_f32_16x16x32_bf16 v[80:83], v[136:139], v[184:187], v[80:83]
	v_mfma_f32_16x16x32_bf16 v[124:127], v[132:135], v[164:167], v[124:127]
	v_mfma_f32_16x16x32_bf16 v[120:123], v[140:143], v[164:167], v[120:123]
	v_mfma_f32_16x16x32_bf16 v[116:119], v[132:135], v[172:175], v[116:119]
	v_mfma_f32_16x16x32_bf16 v[112:115], v[140:143], v[172:175], v[112:115]
	v_mfma_f32_16x16x32_bf16 v[100:103], v[132:135], v[180:183], v[100:103]
	v_mfma_f32_16x16x32_bf16 v[96:99], v[140:143], v[180:183], v[96:99]
	v_mfma_f32_16x16x32_bf16 v[84:87], v[132:135], v[188:191], v[84:87]
	v_mfma_f32_16x16x32_bf16 v[80:83], v[140:143], v[188:191], v[80:83]
	v_mfma_f32_16x16x32_bf16 v[108:111], v[144:147], v[160:163], v[108:111]
	v_mfma_f32_16x16x32_bf16 v[104:107], v[152:155], v[160:163], v[104:107]
	v_mfma_f32_16x16x32_bf16 v[92:95], v[144:147], v[168:171], v[92:95]
	v_mfma_f32_16x16x32_bf16 v[88:91], v[152:155], v[168:171], v[88:91]
	v_mfma_f32_16x16x32_bf16 v[76:79], v[144:147], v[176:179], v[76:79]
	v_mfma_f32_16x16x32_bf16 v[72:75], v[152:155], v[176:179], v[72:75]
	v_mfma_f32_16x16x32_bf16 v[68:71], v[144:147], v[184:187], v[68:71]
	v_mfma_f32_16x16x32_bf16 v[64:67], v[152:155], v[184:187], v[64:67]
	v_mfma_f32_16x16x32_bf16 v[108:111], v[148:151], v[164:167], v[108:111]
	v_mfma_f32_16x16x32_bf16 v[104:107], v[156:159], v[164:167], v[104:107]
	v_mfma_f32_16x16x32_bf16 v[92:95], v[148:151], v[172:175], v[92:95]
	v_mfma_f32_16x16x32_bf16 v[88:91], v[156:159], v[172:175], v[88:91]
	v_mfma_f32_16x16x32_bf16 v[76:79], v[148:151], v[180:183], v[76:79]
	v_mfma_f32_16x16x32_bf16 v[72:75], v[156:159], v[180:183], v[72:75]
	v_mfma_f32_16x16x32_bf16 v[68:71], v[148:151], v[188:191], v[68:71]
	v_mfma_f32_16x16x32_bf16 v[64:67], v[156:159], v[188:191], v[64:67]
	s_barrier
; #define PG8_STAGE(bufoff, gbase, voff) do { _Pragma("unroll") for (int _i = 0; _i < 2; ++_i) \
;         __builtin_amdgcn_global_load_lds((const unsigned*)((const char*)(gbase) + (voff)[_i]), (PG8_LAS unsigned*)(lds + (bufoff) + ldsw + _i * 8192), 16, 0, 0); } while (0)
; #define PG8_LDA(dst, b, h) do { _Pragma("unroll") for (int m = 0; m < 4; ++m) _Pragma("unroll") for (int k = 0; k < 2; ++k) dst[m][k] = *(const PG8_LAS bf16x8*)(lds + PG8_SA(b, h) + aoff + m * 2048 + k * 1024); } while (0)
; #define PG8_LDB(dst, b, h) do { _Pragma("unroll") for (int n = 0; n < 2; ++n) _Pragma("unroll") for (int k = 0; k < 2; ++k) dst[n][k] = *(const PG8_LAS bf16x8*)(lds + PG8_SB(b, h) + boff + n * 2048 + k * 1024); } while (0)
; #define PG8_MMA(ai, bj, At, Bt) do { __builtin_amdgcn_s_setprio(1); _Pragma("unroll") for (int m = 0; m < 4; ++m) _Pragma("unroll") for (int n = 0; n < 2; ++n) _Pragma("unroll") for (int k = 0; k < 2; ++k) \
;         acc[ai][bj][m][n] = __builtin_amdgcn_mfma_f32_16x16x32_bf16(Bt[n][k], At[m][k], acc[ai][bj][m][n], 0, 0, 0); __builtin_amdgcn_s_setprio(0); } while (0)
; #define PG8_WAIT_V(n) asm volatile("s_waitcnt vmcnt(" #n ")" ::: "memory")
; #define PG8_WAIT_L(n) asm volatile("s_waitcnt lgkmcnt(" #n ")" ::: "memory")
; #define PG8_BAR __builtin_amdgcn_s_barrier()
; #define PG8_SCHED __builtin_amdgcn_sched_barrier(0)
; template <class Epi, class Sched, bool ALIGN_EPI = false, bool SP2 = false>
; __device__ __forceinline__ void gemm_phase(PG8_LAS unsigned char* lds, const Gemm g, const Sched& S, const Epi& E) {
;     ...
;             PG8_WAIT_V(8); PG8_WAIT_L(0); PG8_BAR; PG8_MMA(0, 0, At, B0); PG8_MMA(0, 1, At, B1); PG8_BAR; PG8_SCHED;
;             PG8_LDA(At, 0, 1); PG8_STAGE(PG8_SB(0, 0), b2, voffB); PG8_STAGE(PG8_SB(0, 1), b2 + hstep, voffB); PG8_STAGE(PG8_SA(0, 0), a2, voffA);
;             PG8_WAIT_V(8); PG8_WAIT_L(0); PG8_BAR; PG8_MMA(1, 0, At, B0); PG8_MMA(1, 1, At, B1); PG8_BAR; PG8_SCHED;
;             PG8_LDB(B0, 1, 0); PG8_LDB(B1, 1, 1); PG8_SCHED; PG8_LDA(At, 1, 0); PG8_STAGE(PG8_SA(0, 1), a2 + hstep, voffA);
;             PG8_WAIT_V(8); PG8_WAIT_L(0); PG8_BAR; PG8_MMA(0, 0, At, B0); PG8_MMA(0, 1, At, B1); PG8_BAR; PG8_SCHED;
	s_add_i32 s33, s33, s91
	v_lshl_add_u64 v[192:193], s[2:3], 0, v[208:209]
	s_mov_b32 m0, s33
	ds_read_b128 v[160:163], v246 offset:16384
	ds_read_b128 v[164:167], v246 offset:17408
	ds_read_b128 v[168:171], v246 offset:18432
	ds_read_b128 v[172:175], v246 offset:19456
	ds_read_b128 v[176:179], v246 offset:20480
	ds_read_b128 v[180:183], v246 offset:21504
	ds_read_b128 v[184:187], v246 offset:22528
	ds_read_b128 v[188:191], v246 offset:23552
	global_load_lds_dwordx4 v[192:193], off
	s_add_i32 m0, s33, 0x2000
	v_lshl_add_u64 v[194:195], s[2:3], 0, v[214:215]
	s_add_u32 s2, s2, s86
	s_addc_u32 s3, s3, 0
	s_add_i32 s0, s0, s91
	global_load_lds_dwordx4 v[194:195], off
	v_lshl_add_u64 v[196:197], s[2:3], 0, v[208:209]
	s_mov_b32 m0, s0
	v_lshl_add_u64 v[198:199], s[2:3], 0, v[214:215]
	global_load_lds_dwordx4 v[196:197], off
	s_add_i32 m0, s0, 0x2000
	v_lshl_add_u64 v[200:201], s[14:15], 0, v[210:211]
	global_load_lds_dwordx4 v[198:199], off
	s_mov_b32 m0, s20
	v_lshl_add_u64 v[202:203], s[14:15], 0, v[212:213]
	global_load_lds_dwordx4 v[200:201], off
	s_mov_b32 m0, s99
	s_nop 0
	global_load_lds_dwordx4 v[202:203], off
	s_waitcnt vmcnt(8)
	s_waitcnt lgkmcnt(0)
	s_barrier
	s_waitcnt lgkmcnt(0)
	v_mfma_f32_16x16x32_bf16 v[60:63], v[128:131], v[160:163], v[60:63]
	v_mfma_f32_16x16x32_bf16 v[56:59], v[136:139], v[160:163], v[56:59]
	v_mfma_f32_16x16x32_bf16 v[52:55], v[128:131], v[168:171], v[52:55]
	v_mfma_f32_16x16x32_bf16 v[44:47], v[136:139], v[168:171], v[44:47]
	v_mfma_f32_16x16x32_bf16 v[36:39], v[128:131], v[176:179], v[36:39]
	v_mfma_f32_16x16x32_bf16 v[28:31], v[136:139], v[176:179], v[28:31]
	v_mfma_f32_16x16x32_bf16 v[20:23], v[128:131], v[184:187], v[20:23]
	v_mfma_f32_16x16x32_bf16 v[12:15], v[136:139], v[184:187], v[12:15]
	v_mfma_f32_16x16x32_bf16 v[60:63], v[132:135], v[164:167], v[60:63]
	v_mfma_f32_16x16x32_bf16 v[56:59], v[140:143], v[164:167], v[56:59]
	v_mfma_f32_16x16x32_bf16 v[52:55], v[132:135], v[172:175], v[52:55]
	v_mfma_f32_16x16x32_bf16 v[44:47], v[140:143], v[172:175], v[44:47]
	v_mfma_f32_16x16x32_bf16 v[36:39], v[132:135], v[180:183], v[36:39]
	v_mfma_f32_16x16x32_bf16 v[28:31], v[140:143], v[180:183], v[28:31]
	v_mfma_f32_16x16x32_bf16 v[20:23], v[132:135], v[188:191], v[20:23]
	v_mfma_f32_16x16x32_bf16 v[12:15], v[140:143], v[188:191], v[12:15]
	v_mfma_f32_16x16x32_bf16 v[48:51], v[144:147], v[160:163], v[48:51]
	v_mfma_f32_16x16x32_bf16 v[40:43], v[152:155], v[160:163], v[40:43]
	v_mfma_f32_16x16x32_bf16 v[32:35], v[144:147], v[168:171], v[32:35]
	v_mfma_f32_16x16x32_bf16 v[24:27], v[152:155], v[168:171], v[24:27]
	v_mfma_f32_16x16x32_bf16 v[16:19], v[144:147], v[176:179], v[16:19]
	v_mfma_f32_16x16x32_bf16 v[8:11], v[152:155], v[176:179], v[8:11]
	v_mfma_f32_16x16x32_bf16 v[4:7], v[144:147], v[184:187], v[4:7]
	v_mfma_f32_16x16x32_bf16 v[0:3], v[152:155], v[184:187], v[0:3]
	v_mfma_f32_16x16x32_bf16 v[48:51], v[148:151], v[164:167], v[48:51]
	v_mfma_f32_16x16x32_bf16 v[40:43], v[156:159], v[164:167], v[40:43]
	v_mfma_f32_16x16x32_bf16 v[32:35], v[148:151], v[172:175], v[32:35]
	v_mfma_f32_16x16x32_bf16 v[24:27], v[156:159], v[172:175], v[24:27]
	v_mfma_f32_16x16x32_bf16 v[16:19], v[148:151], v[180:183], v[16:19]
	v_mfma_f32_16x16x32_bf16 v[8:11], v[156:159], v[180:183], v[8:11]
	v_mfma_f32_16x16x32_bf16 v[4:7], v[148:151], v[188:191], v[4:7]
	v_mfma_f32_16x16x32_bf16 v[0:3], v[156:159], v[188:191], v[0:3]
	s_barrier
	s_add_i32 s0, 0, 0x18000
	s_add_i32 s33, 0, 0x1c000
	v_add_u32_e32 v140, s0, v252
	v_add_u32_e32 v156, s33, v252
	ds_read_b128 v[128:131], v140
	ds_read_b128 v[132:135], v140 offset:1024
	ds_read_b128 v[136:139], v140 offset:2048
	ds_read_b128 v[140:143], v140 offset:3072
	ds_read_b128 v[144:147], v156
	ds_read_b128 v[148:151], v156 offset:1024
	ds_read_b128 v[152:155], v156 offset:2048
	ds_read_b128 v[156:159], v156 offset:3072
	s_add_u32 s2, s14, s86
	s_addc_u32 s3, s15, 0
	s_mov_b32 m0, s39
	v_lshl_add_u64 v[204:205], s[2:3], 0, v[210:211]
	ds_read_b128 v[160:163], v246 offset:32768
	ds_read_b128 v[164:167], v246 offset:33792
	ds_read_b128 v[168:171], v246 offset:34816
	ds_read_b128 v[172:175], v246 offset:35840
	ds_read_b128 v[176:179], v246 offset:36864
	ds_read_b128 v[180:183], v246 offset:37888
	ds_read_b128 v[184:187], v246 offset:38912
	ds_read_b128 v[188:191], v246 offset:39936
	global_load_lds_dwordx4 v[204:205], off
	v_lshl_add_u64 v[204:205], s[2:3], 0, v[212:213]
	s_mov_b32 m0, s44
	s_nop 0
	global_load_lds_dwordx4 v[204:205], off
	s_waitcnt vmcnt(8)
	s_waitcnt lgkmcnt(0)
	s_barrier
; #define PG8_STAGE(bufoff, gbase, voff) do { _Pragma("unroll") for (int _i = 0; _i < 2; ++_i) \
;         __builtin_amdgcn_global_load_lds((const unsigned*)((const char*)(gbase) + (voff)[_i]), (PG8_LAS unsigned*)(lds + (bufoff) + ldsw + _i * 8192), 16, 0, 0); } while (0)
; #define PG8_WAIT_V(n) asm volatile("s_waitcnt vmcnt(" #n ")" ::: "memory")
; #define PG8_WAIT_L(n) asm volatile("s_waitcnt lgkmcnt(" #n ")" ::: "memory")
; template <class Epi, class Sched, bool ALIGN_EPI = false, bool SP2 = false>
; __device__ __forceinline__ void gemm_phase(PG8_LAS unsigned char* lds, const Gemm g, const Sched& S, const Epi& E) {
;     ...
;             PG8_WAIT_V(8); PG8_WAIT_L(0); PG8_BAR; PG8_MMA(0, 0, At, B0); PG8_MMA(0, 1, At, B1); PG8_BAR; PG8_SCHED;
;             PG8_LDA(At, 1, 1); PG8_STAGE(PG8_SB(1, 0), b3, voffB); PG8_STAGE(PG8_SB(1, 1), b3 + hstep, voffB); PG8_STAGE(PG8_SA(1, 0), a3, voffA);
;             PG8_WAIT_V(8); PG8_WAIT_L(0); PG8_BAR; PG8_MMA(1, 0, At, B0); PG8_MMA(1, 1, At, B1); PG8_BAR; PG8_SCHED;
;             } else {
;             PG8_LDB(B0, 0, 0); PG8_SCHED; PG8_LDA(At, 0, 0); PG8_STAGE(PG8_SA(1, 1), a1 + hstep, voffA);
;             PG8_WAIT_L(8); PG8_BAR; PG8_WAIT_L(0); PG8_MMA(0, 0, At, B0); PG8_BAR; PG8_SCHED;
;             PG8_LDB(B1, 0, 1); PG8_STAGE(PG8_SB(0, 0), b2, voffB);
;             PG8_BAR; PG8_WAIT_L(0); PG8_MMA(0, 1, At, B1); PG8_BAR;
;             PG8_LDA(At, 0, 1); PG8_STAGE(PG8_SA(0, 0), a2, voffA);
;             PG8_BAR; PG8_WAIT_L(0); PG8_MMA(1, 0, At, B0); PG8_BAR; PG8_SCHED;
;             PG8_STAGE(PG8_SB(0, 1), b2 + hstep, voffB);
;             PG8_WAIT_V(6); PG8_BAR; PG8_MMA(1, 1, At, B1); PG8_BAR;
;             PG8_LDB(B0, 1, 0); PG8_SCHED; PG8_LDA(At, 1, 0); PG8_STAGE(PG8_SA(0, 1), a2 + hstep, voffA);
;             PG8_WAIT_L(8); PG8_BAR; PG8_WAIT_L(0); PG8_MMA(0, 0, At, B0); PG8_BAR; PG8_SCHED;
;             PG8_LDB(B1, 1, 1); PG8_STAGE(PG8_SB(1, 0), b3, voffB);
;             PG8_BAR; PG8_WAIT_L(0); PG8_MMA(0, 1, At, B1); PG8_BAR;
;             PG8_LDA(At, 1, 1); PG8_STAGE(PG8_SA(1, 0), a3, voffA);
;             PG8_BAR; PG8_WAIT_L(0); PG8_MMA(1, 0, At, B0); PG8_BAR; PG8_SCHED;
;             PG8_STAGE(PG8_SB(1, 1), b3 + hstep, voffB);
;             PG8_WAIT_V(6); PG8_BAR; PG8_MMA(1, 1, At, B1); PG8_BAR;
;             }
;         }
;         if constexpr (ALIGN_EPI) { if (wr == 0) PG8_BAR; }
	s_waitcnt lgkmcnt(0)
	v_mfma_f32_16x16x32_bf16 v[124:127], v[128:131], v[160:163], v[124:127]
	v_mfma_f32_16x16x32_bf16 v[120:123], v[136:139], v[160:163], v[120:123]
	v_mfma_f32_16x16x32_bf16 v[116:119], v[128:131], v[168:171], v[116:119]
	v_mfma_f32_16x16x32_bf16 v[112:115], v[136:139], v[168:171], v[112:115]
	v_mfma_f32_16x16x32_bf16 v[100:103], v[128:131], v[176:179], v[100:103]
	v_mfma_f32_16x16x32_bf16 v[96:99], v[136:139], v[176:179], v[96:99]
	v_mfma_f32_16x16x32_bf16 v[84:87], v[128:131], v[184:187], v[84:87]
	v_mfma_f32_16x16x32_bf16 v[80:83], v[136:139], v[184:187], v[80:83]
	v_mfma_f32_16x16x32_bf16 v[124:127], v[132:135], v[164:167], v[124:127]
	v_mfma_f32_16x16x32_bf16 v[120:123], v[140:143], v[164:167], v[120:123]
	v_mfma_f32_16x16x32_bf16 v[116:119], v[132:135], v[172:175], v[116:119]
	v_mfma_f32_16x16x32_bf16 v[112:115], v[140:143], v[172:175], v[112:115]
	v_mfma_f32_16x16x32_bf16 v[100:103], v[132:135], v[180:183], v[100:103]
	v_mfma_f32_16x16x32_bf16 v[96:99], v[140:143], v[180:183], v[96:99]
	v_mfma_f32_16x16x32_bf16 v[84:87], v[132:135], v[188:191], v[84:87]
	v_mfma_f32_16x16x32_bf16 v[80:83], v[140:143], v[188:191], v[80:83]
	v_mfma_f32_16x16x32_bf16 v[108:111], v[144:147], v[160:163], v[108:111]
	v_mfma_f32_16x16x32_bf16 v[104:107], v[152:155], v[160:163], v[104:107]
	v_mfma_f32_16x16x32_bf16 v[92:95], v[144:147], v[168:171], v[92:95]
	v_mfma_f32_16x16x32_bf16 v[88:91], v[152:155], v[168:171], v[88:91]
	v_mfma_f32_16x16x32_bf16 v[76:79], v[144:147], v[176:179], v[76:79]
	v_mfma_f32_16x16x32_bf16 v[72:75], v[152:155], v[176:179], v[72:75]
	v_mfma_f32_16x16x32_bf16 v[68:71], v[144:147], v[184:187], v[68:71]
	v_mfma_f32_16x16x32_bf16 v[64:67], v[152:155], v[184:187], v[64:67]
	v_mfma_f32_16x16x32_bf16 v[108:111], v[148:151], v[164:167], v[108:111]
	v_mfma_f32_16x16x32_bf16 v[104:107], v[156:159], v[164:167], v[104:107]
	v_mfma_f32_16x16x32_bf16 v[92:95], v[148:151], v[172:175], v[92:95]
	v_mfma_f32_16x16x32_bf16 v[88:91], v[156:159], v[172:175], v[88:91]
	v_mfma_f32_16x16x32_bf16 v[76:79], v[148:151], v[180:183], v[76:79]
	v_mfma_f32_16x16x32_bf16 v[72:75], v[156:159], v[180:183], v[72:75]
	v_mfma_f32_16x16x32_bf16 v[68:71], v[148:151], v[188:191], v[68:71]
	v_mfma_f32_16x16x32_bf16 v[64:67], v[156:159], v[188:191], v[64:67]
	s_barrier
	s_add_i32 s0, s0, s91
	v_lshl_add_u64 v[192:193], v[192:193], 0, s[66:67]
	s_mov_b32 m0, s0
	ds_read_b128 v[160:163], v246 offset:49152
	ds_read_b128 v[164:167], v246 offset:50176
	ds_read_b128 v[168:171], v246 offset:51200
	ds_read_b128 v[172:175], v246 offset:52224
	ds_read_b128 v[176:179], v246 offset:53248
	ds_read_b128 v[180:183], v246 offset:54272
	ds_read_b128 v[184:187], v246 offset:55296
	ds_read_b128 v[188:191], v246 offset:56320
	global_load_lds_dwordx4 v[192:193], off
	v_lshl_add_u64 v[192:193], v[194:195], 0, s[66:67]
	s_add_i32 m0, s0, 0x2000
	s_add_i32 s0, s33, s91
	global_load_lds_dwordx4 v[192:193], off
	v_lshl_add_u64 v[192:193], v[196:197], 0, s[66:67]
	s_mov_b32 m0, s0
	s_nop 0
	global_load_lds_dwordx4 v[192:193], off
	v_lshl_add_u64 v[192:193], v[198:199], 0, s[66:67]
	s_add_i32 m0, s0, 0x2000
	s_nop 0
	global_load_lds_dwordx4 v[192:193], off
	v_lshl_add_u64 v[192:193], v[200:201], 0, s[66:67]
	s_mov_b32 m0, s18
	s_nop 0
	global_load_lds_dwordx4 v[192:193], off
	v_lshl_add_u64 v[192:193], v[202:203], 0, s[66:67]
	s_mov_b32 m0, s19
	s_nop 0
	global_load_lds_dwordx4 v[192:193], off
	s_waitcnt vmcnt(8)
	s_waitcnt lgkmcnt(0)
	s_barrier
	s_waitcnt lgkmcnt(0)
	v_mfma_f32_16x16x32_bf16 v[60:63], v[128:131], v[160:163], v[60:63]
	v_mfma_f32_16x16x32_bf16 v[56:59], v[136:139], v[160:163], v[56:59]
	v_mfma_f32_16x16x32_bf16 v[52:55], v[128:131], v[168:171], v[52:55]
	v_mfma_f32_16x16x32_bf16 v[44:47], v[136:139], v[168:171], v[44:47]
	v_mfma_f32_16x16x32_bf16 v[36:39], v[128:131], v[176:179], v[36:39]
	v_mfma_f32_16x16x32_bf16 v[28:31], v[136:139], v[176:179], v[28:31]
	v_mfma_f32_16x16x32_bf16 v[20:23], v[128:131], v[184:187], v[20:23]
	v_mfma_f32_16x16x32_bf16 v[12:15], v[136:139], v[184:187], v[12:15]
	v_mfma_f32_16x16x32_bf16 v[60:63], v[132:135], v[164:167], v[60:63]
	v_mfma_f32_16x16x32_bf16 v[56:59], v[140:143], v[164:167], v[56:59]
	v_mfma_f32_16x16x32_bf16 v[52:55], v[132:135], v[172:175], v[52:55]
	v_mfma_f32_16x16x32_bf16 v[44:47], v[140:143], v[172:175], v[44:47]
	v_mfma_f32_16x16x32_bf16 v[36:39], v[132:135], v[180:183], v[36:39]
	v_mfma_f32_16x16x32_bf16 v[28:31], v[140:143], v[180:183], v[28:31]
	v_mfma_f32_16x16x32_bf16 v[20:23], v[132:135], v[188:191], v[20:23]
	v_mfma_f32_16x16x32_bf16 v[12:15], v[140:143], v[188:191], v[12:15]
	v_mfma_f32_16x16x32_bf16 v[48:51], v[144:147], v[160:163], v[48:51]
	v_mfma_f32_16x16x32_bf16 v[40:43], v[152:155], v[160:163], v[40:43]
	v_mfma_f32_16x16x32_bf16 v[32:35], v[144:147], v[168:171], v[32:35]
	v_mfma_f32_16x16x32_bf16 v[24:27], v[152:155], v[168:171], v[24:27]
	v_mfma_f32_16x16x32_bf16 v[16:19], v[144:147], v[176:179], v[16:19]
	v_mfma_f32_16x16x32_bf16 v[8:11], v[152:155], v[176:179], v[8:11]
	v_mfma_f32_16x16x32_bf16 v[4:7], v[144:147], v[184:187], v[4:7]
	v_mfma_f32_16x16x32_bf16 v[0:3], v[152:155], v[184:187], v[0:3]
	v_mfma_f32_16x16x32_bf16 v[48:51], v[148:151], v[164:167], v[48:51]
	v_mfma_f32_16x16x32_bf16 v[40:43], v[156:159], v[164:167], v[40:43]
	v_mfma_f32_16x16x32_bf16 v[32:35], v[148:151], v[172:175], v[32:35]
	v_mfma_f32_16x16x32_bf16 v[24:27], v[156:159], v[172:175], v[24:27]
	v_mfma_f32_16x16x32_bf16 v[16:19], v[148:151], v[180:183], v[16:19]
	v_mfma_f32_16x16x32_bf16 v[8:11], v[156:159], v[180:183], v[8:11]
	v_mfma_f32_16x16x32_bf16 v[4:7], v[148:151], v[188:191], v[4:7]
	v_mfma_f32_16x16x32_bf16 v[0:3], v[156:159], v[188:191], v[0:3]
	s_barrier
	s_add_u32 s12, s12, 0x100
	s_addc_u32 s13, s13, 0
	s_add_u32 s16, s16, 0x100
	s_addc_u32 s17, s17, 0
	s_cmp_ge_u32 s1, s45
	s_mov_b32 s0, s1
	s_cbranch_scc0 .LBB0_186
	s_and_b64 vcc, exec, s[92:93]
	s_cbranch_vccz .LBB0_189
	s_barrier
;     __device__ __forceinline__ void operator()(const f32x4 (&acc)[2][2][4][2], const Unit& u, int wr, int wc, int fr, int fq) const {
;         bf16_t* Y = (bf16_t*)(ws + WS_Y);
;         const int row0 = u.pm * BM + wr * 64 + fr;
;         if (u.pn >= 2) { EpiStore E{Y, INP}; E(acc, u, wr, wc, fr, fq); return; }
; #pragma unroll
;         for (int ai = 0; ai < 2; ++ai)
; #pragma unroll
;             for (int m = 0; m < 4; ++m) {
;                 float s[2];
; #pragma unroll
;                 for (int bj = 0; bj < 2; ++bj) { const f32x4 a = acc[ai][bj][m][0], b = acc[ai][bj][m][1];
;                     float t = ((a[0] * a[0] + a[1] * a[1]) + (a[2] * a[2] + a[3] * a[3])) + ((b[0] * b[0] + b[1] * b[1]) + (b[2] * b[2] + b[3] * b[3]));
;                     t += __shfl_xor(t, 16); t += __shfl_xor(t, 32); s[bj] = t; }
;                 if (fq == 0) { const int xr = (ai * HALF + wr * 64 + m * 16 + fr) * 8; X[xr + wc] = s[0]; X[xr + 4 + wc] = s[1]; } }
;     __device__ __forceinline__ void operator()(const f32x4 (&acc)[2][2][4][2], const Unit& u, int wr, int wc, int fr_, int fq_) const {
;         int ln = (int)__builtin_amdgcn_mbcnt_hi(~0u, __builtin_amdgcn_mbcnt_lo(~0u, 0u)); asm volatile("" : "+v"(ln));
;         const int fr = ln & 15, fq = ln >> 4; (void)fr_; (void)fq_;
;         if (mode == 0) { EpiStore E{(bf16_t*)a0, ldc}; E(acc, u, wr, wc, fr, fq); }
;         else if (mode == 1) { EpiResid E{(const float*)a0, (const float*)a1, (float*)a2, (float*)a3, (const float*)a4, 0, (bf16_t*)x1a, (bf16_t*)x1b, ldc}; E(acc, u, wr, wc, fr, fq); }
;         else if (mode == 2) { EpiFfUp E{(bf16_t*)a0, (const float*)a1, (float*)a2, (float*)a2 + EDGE_N, (float*)a2 + 2 * EDGE_N}; E(acc, u, wr, wc, fr, fq); }
;         else if (mode == 3) { EpiPartial E{(float*)a3}; E(acc, u, wr, wc, fr, fq); }
;         else if (mode == 4) { EpiKv E{(bf16_t*)a0, (const float*)a1, (__attribute__((address_space(3))) float*)(131072u)}; E(acc, u, wr, wc, fr, fq); }
;         else { EpiIn E{(unsigned char*)a0, (const float*)a1, (const float*)a2, (const float*)a3, (__attribute__((address_space(3))) float*)(131072u)}; E(acc, u, wr, wc, fr, fq); }
.LBB0_189:
	s_setprio 0
	v_mov_b32_e32 v166, v245
	s_cmp_lt_i32 s57, 2
	v_and_b32_e32 v250, 15, v166
	v_ashrrev_i32_e32 v249, 4, v166
	s_mov_b64 s[12:13], -1
	s_cbranch_scc1 .LBB0_286
	s_cmp_lt_i32 s57, 3
	s_cbranch_scc1 .LBB0_275
	s_cmp_lt_i32 s57, 4
	s_cbranch_scc1 .LBB0_272
	s_cmp_lg_u32 s57, 4
	s_cbranch_scc0 .LBB0_265
	s_lshl_b32 s36, s48, 8
	s_add_i32 s36, s36, s74
	v_or_b32_e32 v144, s36, v250
	s_cmp_gt_i32 s38, 1
	s_cbranch_scc1 .LBB0_262
	v_mul_f32_e32 v131, v125, v125
	v_mul_f32_e32 v132, v127, v127
	v_fmac_f32_e32 v131, v124, v124
	v_fmac_f32_e32 v132, v126, v126
	v_add_f32_e32 v131, v131, v132
	v_mul_f32_e32 v132, v121, v121
	v_mul_f32_e32 v133, v123, v123
	v_fmac_f32_e32 v132, v120, v120
	v_fmac_f32_e32 v133, v122, v122
	v_add_f32_e32 v132, v132, v133
	v_mul_f32_e32 v133, v109, v109
	v_mul_f32_e32 v134, v111, v111
	v_and_b32_e32 v129, 64, v245
	v_fmac_f32_e32 v133, v108, v108
	v_fmac_f32_e32 v134, v110, v110
	v_xor_b32_e32 v128, 16, v245
	v_add_u32_e32 v129, 64, v129
	v_add_f32_e32 v133, v133, v134
	v_mul_f32_e32 v134, v105, v105
	v_mul_f32_e32 v135, v107, v107
	v_cmp_lt_i32_e32 vcc, v128, v129
	v_fmac_f32_e32 v134, v104, v104
	v_fmac_f32_e32 v135, v106, v106
	v_cndmask_b32_e32 v128, v245, v128, vcc
	v_add_f32_e32 v134, v134, v135
	v_lshlrev_b32_e32 v128, 2, v128
	v_add_f32_e32 v131, v131, v132
	v_add_f32_e32 v133, v133, v134
	ds_bpermute_b32 v132, v128, v131
	ds_bpermute_b32 v134, v128, v133
	v_xor_b32_e32 v130, 32, v245
	v_cmp_lt_i32_e32 vcc, v130, v129
	v_or_b32_e32 v167, s74, v250
	v_readlane_b32 s0, v255, 10
	v_cndmask_b32_e32 v129, v245, v130, vcc
	v_lshlrev_b32_e32 v141, 2, v129
	s_waitcnt lgkmcnt(0)
	v_add_f32_e32 v130, v131, v132
	v_add_f32_e32 v132, v133, v134
	ds_bpermute_b32 v131, v141, v130
	ds_bpermute_b32 v133, v141, v132
	v_cmp_gt_u32_e32 vcc, 16, v166
	v_lshl_add_u32 v129, v167, 5, s0
	s_and_saveexec_b64 s[12:13], vcc
	s_cbranch_execz .LBB0_196
	s_waitcnt lgkmcnt(0)
	v_add_f32_e32 v130, v130, v131
	v_add_f32_e32 v131, v132, v133
	ds_write2_b32 v129, v130, v131 offset1:4
